# v9 + dead shuffle-index arithmetic removed + GEMM4a epilogue SSKV prefetch with counted wait
# speedup vs baseline: 1.0100x; 1.0044x over previous
.LBB0_507:
	s_lshl_b32 s37, s44, 8
	v_mbcnt_lo_u32_b32 v205, -1, 0
	v_mbcnt_hi_u32_b32 v205, -1, v205
	s_add_i32 s37, s37, s60
	v_ashrrev_i32_e32 v214, 3, v205
	v_add_u32_e32 v104, s37, v214
	v_ashrrev_i32_e32 v105, 31, v104
	s_lshl_b32 s44, s10, 8
	v_lshlrev_b64 v[104:105], 10, v[104:105]
	s_ashr_i32 s45, s44, 31
	v_lshl_add_u64 v[196:197], v[104:105], 0, s[44:45]
	v_or_b32_e32 v104, s66, v196
	v_lshlrev_b32_e32 v105, 3, v205
	v_and_or_b32 v196, v105, 56, v104
	v_lshl_add_u64 v[104:105], v[196:197], 1, s[16:17]
	v_add_co_u32_e32 v106, vcc, s58, v104
	v_mul_lo_u32 v214, v214, s68
	s_nop 0
	v_addc_co_u32_e32 v107, vcc, 0, v105, vcc
	global_load_dwordx4 v[206:209], v[104:105], off nt
	global_load_dwordx4 v[210:213], v[106:107], off nt
	v_add_co_u32_e32 v106, vcc, s64, v104
	v_lshlrev_b32_e32 v205, 4, v205
	s_nop 0
	v_addc_co_u32_e32 v107, vcc, 0, v105, vcc
	v_add_co_u32_e32 v108, vcc, s71, v104
	v_add_u32_e32 v214, s67, v214
	s_nop 0
	v_addc_co_u32_e32 v109, vcc, 0, v105, vcc
	global_load_dwordx4 v[176:179], v[106:107], off nt
	global_load_dwordx4 v[180:183], v[108:109], off nt
	v_add_co_u32_e32 v106, vcc, s56, v104
	v_and_b32_e32 v205, 0x70, v205
	s_nop 0
	v_addc_co_u32_e32 v107, vcc, 0, v105, vcc
	v_add_co_u32_e32 v108, vcc, s57, v104
	v_add_u32_e32 v205, v214, v205
	s_nop 0
	v_addc_co_u32_e32 v109, vcc, 0, v105, vcc
	global_load_dwordx4 v[168:171], v[106:107], off nt
	global_load_dwordx4 v[172:175], v[108:109], off nt
	v_add_co_u32_e32 v106, vcc, s63, v104
	s_lshl_b32 s44, s10, 2
	s_nop 0
	v_addc_co_u32_e32 v107, vcc, 0, v105, vcc
	v_add_co_u32_e32 v108, vcc, s65, v104
	s_ashr_i32 s45, s44, 31
	s_nop 0
	v_addc_co_u32_e32 v109, vcc, 0, v105, vcc
	global_load_dwordx4 v[160:163], v[106:107], off nt
	global_load_dwordx4 v[164:167], v[108:109], off nt
	v_add_co_u32_e32 v106, vcc, s72, v104
	s_nop 1
	v_addc_co_u32_e32 v107, vcc, 0, v105, vcc
	v_add_co_u32_e32 v108, vcc, s73, v104
	s_nop 1
	v_addc_co_u32_e32 v109, vcc, 0, v105, vcc
	global_load_dwordx4 v[152:155], v[106:107], off nt
	global_load_dwordx4 v[156:159], v[108:109], off nt
	v_add_co_u32_e32 v106, vcc, s74, v104
	s_nop 1
	v_addc_co_u32_e32 v107, vcc, 0, v105, vcc
	v_add_co_u32_e32 v108, vcc, s75, v104
	s_nop 1
	v_addc_co_u32_e32 v109, vcc, 0, v105, vcc
	global_load_dwordx4 v[144:147], v[106:107], off nt
	global_load_dwordx4 v[148:151], v[108:109], off nt
	v_add_co_u32_e32 v106, vcc, s79, v104
	s_nop 1
	v_addc_co_u32_e32 v107, vcc, 0, v105, vcc
	v_add_co_u32_e32 v108, vcc, s80, v104
	s_nop 1
	v_addc_co_u32_e32 v109, vcc, 0, v105, vcc
	global_load_dwordx4 v[124:127], v[106:107], off nt
	global_load_dwordx4 v[128:131], v[108:109], off nt
	v_add_co_u32_e32 v106, vcc, s81, v104
	s_nop 1
	v_addc_co_u32_e32 v107, vcc, 0, v105, vcc
	v_add_co_u32_e32 v108, vcc, s82, v104
	s_nop 1
	v_addc_co_u32_e32 v109, vcc, 0, v105, vcc
	global_load_dwordx4 v[104:107], v[106:107], off nt
	s_nop 0
	global_load_dwordx4 v[108:111], v[108:109], off nt
	s_waitcnt vmcnt(0)
	ds_write_b128 v205, v[206:209]
	ds_write_b128 v205, v[210:213] offset:1152
	ds_read_b128 v[206:209], v204
	ds_read_b128 v[210:213], v204 offset:64
	s_waitcnt lgkmcnt(1)
	v_lshlrev_b32_e32 v214, 16, v206
	v_and_b32_e32 v206, 0xffff0000, v206
	v_add_f32_e32 v206, v141, v206
	v_lshlrev_b32_e32 v141, 16, v207
	v_add_f32_e32 v141, v142, v141
	v_and_b32_e32 v142, 0xffff0000, v207
	v_add_f32_e32 v143, v143, v142
	v_lshlrev_b32_e32 v142, 16, v208
	v_add_f32_e32 v142, v136, v142
	v_and_b32_e32 v136, 0xffff0000, v208
	v_add_f32_e32 v207, v137, v136
	v_lshlrev_b32_e32 v136, 16, v209
	v_add_f32_e32 v138, v138, v136
	v_and_b32_e32 v136, 0xffff0000, v209
	v_add_f32_e32 v209, v139, v136
	s_waitcnt lgkmcnt(0)
	v_lshlrev_b32_e32 v136, 16, v210
	v_add_f32_e32 v136, v132, v136
	v_and_b32_e32 v132, 0xffff0000, v210
	v_add_f32_e32 v137, v133, v132
	v_lshlrev_b32_e32 v132, 16, v211
	v_add_f32_e32 v134, v134, v132
	v_and_b32_e32 v132, 0xffff0000, v211
	v_add_f32_e32 v139, v135, v132
	v_lshlrev_b32_e32 v132, 16, v212
	v_add_f32_e32 v135, v120, v132
	v_and_b32_e32 v120, 0xffff0000, v212
	v_add_f32_e32 v208, v121, v120
	v_lshlrev_b32_e32 v120, 16, v213
	v_add_f32_e32 v122, v122, v120
	v_and_b32_e32 v120, 0xffff0000, v213
	v_add_f32_e32 v140, v140, v214
	v_add_f32_e32 v123, v123, v120
	v_mul_f32_e32 v120, v206, v206
	v_mul_f32_e32 v121, v143, v143
	v_fmac_f32_e32 v120, v140, v140
	v_fmac_f32_e32 v121, v141, v141
	v_add_f32_e32 v120, v120, v121
	v_mul_f32_e32 v121, v207, v207
	v_mul_f32_e32 v132, v209, v209
	v_fmac_f32_e32 v121, v142, v142
	v_fmac_f32_e32 v132, v138, v138
	v_add_f32_e32 v121, v121, v132
	v_add_f32_e32 v120, v120, v121
	v_mul_f32_e32 v121, v137, v137
	v_mul_f32_e32 v132, v139, v139
	v_fmac_f32_e32 v121, v136, v136
	v_fmac_f32_e32 v132, v134, v134
	v_add_f32_e32 v121, v121, v132
	v_mul_f32_e32 v132, v208, v208
	v_mul_f32_e32 v133, v123, v123
	v_fmac_f32_e32 v132, v135, v135
	v_fmac_f32_e32 v133, v122, v122
	v_add_f32_e32 v132, v132, v133
	v_add_f32_e32 v121, v121, v132
	v_and_b32_e32 v132, 64, v203
	v_add_f32_e32 v121, v120, v121
	v_add_u32_e32 v133, 64, v132
	v_mov_b32_e32 v210, v121
	s_nop 1
	v_permlane16_swap_b32_e32 v121, v210
	v_or_b32_e32 v120, s37, v198
	s_waitcnt lgkmcnt(0)
	v_add_f32_e32 v210, v121, v210
	v_xor_b32_e32 v121, 32, v203
	v_cmp_lt_i32_e32 vcc, v121, v133
	s_nop 1
	v_cndmask_b32_e32 v121, v203, v121, vcc
	v_lshlrev_b32_e32 v133, 2, v121
	v_mov_b32_e32 v211, v210
	s_nop 1
	v_permlane32_swap_b32_e32 v210, v211
	s_and_saveexec_b64 s[46:47], s[4:5]
	s_cbranch_execz .LBB0_509
	v_ashrrev_i32_e32 v121, 31, v120
	v_lshlrev_b64 v[212:213], 6, v[120:121]
	v_lshl_add_u64 v[212:213], s[18:19], 0, v[212:213]
	v_lshl_add_u64 v[212:213], s[44:45], 2, v[212:213]
	s_lshl_b32 s10, s59, 2
	v_lshl_add_u64 v[212:213], v[212:213], 0, s[10:11]
	s_waitcnt lgkmcnt(0)
	v_add_f32_e32 v121, v210, v211
	global_store_dword v[212:213], v121, off

.LBB0_574:
	s_lshl_b32 s10, s10, 2
	s_add_i32 s66, s10, -4
	s_andn2_b64 vcc, exec, s[68:69]
	s_ashr_i32 s67, s66, 31
	s_cbranch_vccnz .LBB0_580
	v_mul_f32_e32 v128, v125, v125
	v_mul_f32_e32 v129, v127, v127
	v_fmac_f32_e32 v128, v124, v124
	v_fmac_f32_e32 v129, v126, v126
	v_add_f32_e32 v128, v128, v129
	v_mul_f32_e32 v129, v121, v121
	v_mul_f32_e32 v130, v123, v123
	v_fmac_f32_e32 v129, v120, v120
	v_fmac_f32_e32 v130, v122, v122
	v_add_f32_e32 v129, v129, v130
	v_add_f32_e32 v128, v128, v129
	v_mul_f32_e32 v129, v117, v117
	v_mul_f32_e32 v130, v119, v119
	v_fmac_f32_e32 v129, v116, v116
	v_fmac_f32_e32 v130, v118, v118
	v_add_f32_e32 v129, v129, v130
	v_mul_f32_e32 v130, v113, v113
	v_mul_f32_e32 v131, v115, v115
	v_fmac_f32_e32 v130, v112, v112
	v_fmac_f32_e32 v131, v114, v114
	v_add_f32_e32 v130, v130, v131
	v_add_f32_e32 v129, v129, v130
	v_and_b32_e32 v130, 64, v191
	v_add_f32_e32 v128, v128, v129
	v_add_u32_e32 v130, 64, v130
	v_mov_b32_e32 v129, v128
	s_nop 1
	v_permlane16_swap_b32_e32 v128, v129
	s_waitcnt lgkmcnt(0)
	v_add_f32_e32 v128, v128, v129
	v_mov_b32_e32 v129, v128
	s_nop 1
	v_permlane32_swap_b32_e32 v128, v129
	s_and_saveexec_b64 s[10:11], s[4:5]
	s_cbranch_execz .LBB0_579
	s_waitcnt lgkmcnt(0)
	v_add_f32_e32 v128, v128, v129
	s_and_b64 vcc, exec, s[64:65]
	s_cbranch_vccz .LBB0_707
	v_lshlrev_b64 v[130:131], 5, v[188:189]
	v_lshl_add_u64 v[130:131], s[40:41], 0, v[130:131]
	v_lshl_add_u64 v[130:131], s[66:67], 2, v[130:131]
	s_lshl_b32 s16, s92, 2
	v_lshl_add_u64 v[130:131], v[130:131], 0, s[16:17]
	global_store_dword v[130:131], v128, off
	s_cbranch_execnz .LBB0_579

.LBB0_590:
	s_andn2_b64 vcc, exec, s[72:73]
	s_cbranch_vccnz .LBB0_596
	v_mul_f32_e32 v112, v109, v109
	v_mul_f32_e32 v113, v111, v111
	v_fmac_f32_e32 v112, v108, v108
	v_fmac_f32_e32 v113, v110, v110
	v_add_f32_e32 v112, v112, v113
	v_mul_f32_e32 v113, v105, v105
	v_mul_f32_e32 v114, v107, v107
	v_fmac_f32_e32 v113, v104, v104
	v_fmac_f32_e32 v114, v106, v106
	v_add_f32_e32 v113, v113, v114
	v_add_f32_e32 v112, v112, v113
	v_mul_f32_e32 v113, v101, v101
	v_mul_f32_e32 v114, v103, v103
	v_fmac_f32_e32 v113, v100, v100
	v_fmac_f32_e32 v114, v102, v102
	v_add_f32_e32 v113, v113, v114
	v_mul_f32_e32 v114, v97, v97
	v_mul_f32_e32 v115, v99, v99
	v_fmac_f32_e32 v114, v96, v96
	v_fmac_f32_e32 v115, v98, v98
	v_add_f32_e32 v114, v114, v115
	v_add_f32_e32 v113, v113, v114
	v_and_b32_e32 v114, 64, v191
	v_add_f32_e32 v112, v112, v113
	v_add_u32_e32 v114, 64, v114
	v_mov_b32_e32 v113, v112
	s_nop 1
	v_permlane16_swap_b32_e32 v112, v113
	s_waitcnt lgkmcnt(0)
	v_add_f32_e32 v112, v112, v113
	v_mov_b32_e32 v113, v112
	s_nop 1
	v_permlane32_swap_b32_e32 v112, v113
	s_and_saveexec_b64 s[72:73], s[4:5]
	s_cbranch_execz .LBB0_595
	s_andn2_b64 vcc, exec, s[64:65]
	s_waitcnt lgkmcnt(0)
	v_add_f32_e32 v112, v112, v113
	s_cbranch_vccnz .LBB0_708
	v_lshlrev_b64 v[114:115], 5, v[184:185]
	v_lshl_add_u64 v[114:115], s[40:41], 0, v[114:115]
	v_lshl_add_u64 v[114:115], s[66:67], 2, v[114:115]
	s_lshl_b32 s16, s92, 2
	v_lshl_add_u64 v[114:115], v[114:115], 0, s[16:17]
	global_store_dword v[114:115], v112, off
	s_cbranch_execnz .LBB0_595

.LBB0_606:
	s_andn2_b64 vcc, exec, s[72:73]
	s_cbranch_vccnz .LBB0_612
	s_waitcnt lgkmcnt(1)
	v_mul_f32_e32 v96, v93, v93
	v_mul_f32_e32 v97, v95, v95
	v_fmac_f32_e32 v96, v92, v92
	v_fmac_f32_e32 v97, v94, v94
	v_add_f32_e32 v96, v96, v97
	v_mul_f32_e32 v97, v89, v89
	v_mul_f32_e32 v98, v91, v91
	v_fmac_f32_e32 v97, v88, v88
	v_fmac_f32_e32 v98, v90, v90
	v_add_f32_e32 v97, v97, v98
	v_add_f32_e32 v96, v96, v97
	v_mul_f32_e32 v97, v85, v85
	v_mul_f32_e32 v98, v87, v87
	v_fmac_f32_e32 v97, v84, v84
	v_fmac_f32_e32 v98, v86, v86
	v_add_f32_e32 v97, v97, v98
	v_mul_f32_e32 v98, v81, v81
	v_mul_f32_e32 v99, v83, v83
	v_fmac_f32_e32 v98, v80, v80
	v_fmac_f32_e32 v99, v82, v82
	v_add_f32_e32 v98, v98, v99
	v_add_f32_e32 v97, v97, v98
	v_and_b32_e32 v98, 64, v191
	v_add_f32_e32 v96, v96, v97
	v_add_u32_e32 v98, 64, v98
	v_mov_b32_e32 v97, v96
	s_nop 1
	v_permlane16_swap_b32_e32 v96, v97
	s_waitcnt lgkmcnt(0)
	v_add_f32_e32 v96, v96, v97
	v_mov_b32_e32 v97, v96
	s_nop 1
	v_permlane32_swap_b32_e32 v96, v97
	s_and_saveexec_b64 s[72:73], s[4:5]
	s_cbranch_execz .LBB0_611
	s_andn2_b64 vcc, exec, s[64:65]
	s_waitcnt lgkmcnt(0)
	v_add_f32_e32 v96, v96, v97
	s_cbranch_vccnz .LBB0_709
	v_lshlrev_b64 v[98:99], 5, v[180:181]
	v_lshl_add_u64 v[98:99], s[40:41], 0, v[98:99]
	v_lshl_add_u64 v[98:99], s[66:67], 2, v[98:99]
	s_lshl_b32 s16, s92, 2
	v_lshl_add_u64 v[98:99], v[98:99], 0, s[16:17]
	global_store_dword v[98:99], v96, off
	s_cbranch_execnz .LBB0_611

.LBB0_622:
	s_andn2_b64 vcc, exec, s[72:73]
	s_cbranch_vccnz .LBB0_628
	s_waitcnt lgkmcnt(1)
	v_mul_f32_e32 v80, v77, v77
	v_mul_f32_e32 v81, v79, v79
	v_fmac_f32_e32 v80, v76, v76
	v_fmac_f32_e32 v81, v78, v78
	v_add_f32_e32 v80, v80, v81
	v_mul_f32_e32 v81, v73, v73
	v_mul_f32_e32 v82, v75, v75
	v_fmac_f32_e32 v81, v72, v72
	v_fmac_f32_e32 v82, v74, v74
	v_add_f32_e32 v81, v81, v82
	v_add_f32_e32 v80, v80, v81
	v_mul_f32_e32 v81, v69, v69
	v_mul_f32_e32 v82, v71, v71
	v_fmac_f32_e32 v81, v68, v68
	v_fmac_f32_e32 v82, v70, v70
	v_add_f32_e32 v81, v81, v82
	v_mul_f32_e32 v82, v65, v65
	v_mul_f32_e32 v83, v67, v67
	v_fmac_f32_e32 v82, v64, v64
	v_fmac_f32_e32 v83, v66, v66
	v_add_f32_e32 v82, v82, v83
	v_add_f32_e32 v81, v81, v82
	v_and_b32_e32 v82, 64, v191
	v_add_f32_e32 v80, v80, v81
	v_add_u32_e32 v82, 64, v82
	v_mov_b32_e32 v81, v80
	s_nop 1
	v_permlane16_swap_b32_e32 v80, v81
	s_waitcnt lgkmcnt(0)
	v_add_f32_e32 v80, v80, v81
	v_mov_b32_e32 v81, v80
	s_nop 1
	v_permlane32_swap_b32_e32 v80, v81
	s_and_saveexec_b64 s[72:73], s[4:5]
	s_cbranch_execz .LBB0_627
	s_andn2_b64 vcc, exec, s[64:65]
	s_waitcnt lgkmcnt(0)
	v_add_f32_e32 v80, v80, v81
	s_cbranch_vccnz .LBB0_710
	v_lshlrev_b64 v[82:83], 5, v[174:175]
	v_lshl_add_u64 v[82:83], s[40:41], 0, v[82:83]
	v_lshl_add_u64 v[82:83], s[66:67], 2, v[82:83]
	s_lshl_b32 s16, s92, 2
	v_lshl_add_u64 v[82:83], v[82:83], 0, s[16:17]
	global_store_dword v[82:83], v80, off
	s_cbranch_execnz .LBB0_627

.LBB0_638:
	s_andn2_b64 vcc, exec, s[72:73]
	s_cbranch_vccnz .LBB0_644
	s_waitcnt lgkmcnt(1)
	v_mul_f32_e32 v64, v61, v61
	v_mul_f32_e32 v65, v63, v63
	v_fmac_f32_e32 v64, v60, v60
	v_fmac_f32_e32 v65, v62, v62
	v_add_f32_e32 v64, v64, v65
	v_mul_f32_e32 v65, v57, v57
	v_mul_f32_e32 v66, v59, v59
	v_fmac_f32_e32 v65, v56, v56
	v_fmac_f32_e32 v66, v58, v58
	v_add_f32_e32 v65, v65, v66
	v_add_f32_e32 v64, v64, v65
	v_mul_f32_e32 v65, v53, v53
	v_mul_f32_e32 v66, v55, v55
	v_fmac_f32_e32 v65, v52, v52
	v_fmac_f32_e32 v66, v54, v54
	v_add_f32_e32 v65, v65, v66
	v_mul_f32_e32 v66, v49, v49
	v_mul_f32_e32 v67, v51, v51
	v_fmac_f32_e32 v66, v48, v48
	v_fmac_f32_e32 v67, v50, v50
	v_add_f32_e32 v66, v66, v67
	v_add_f32_e32 v65, v65, v66
	v_and_b32_e32 v66, 64, v191
	v_add_f32_e32 v64, v64, v65
	v_add_u32_e32 v66, 64, v66
	v_mov_b32_e32 v65, v64
	s_nop 1
	v_permlane16_swap_b32_e32 v64, v65
	s_waitcnt lgkmcnt(0)
	v_add_f32_e32 v64, v64, v65
	v_mov_b32_e32 v65, v64
	s_nop 1
	v_permlane32_swap_b32_e32 v64, v65
	s_and_saveexec_b64 s[72:73], s[4:5]
	s_cbranch_execz .LBB0_643
	s_andn2_b64 vcc, exec, s[64:65]
	s_waitcnt lgkmcnt(0)
	v_add_f32_e32 v64, v64, v65
	s_cbranch_vccnz .LBB0_711
	v_lshlrev_b64 v[66:67], 5, v[170:171]
	v_lshl_add_u64 v[66:67], s[40:41], 0, v[66:67]
	v_lshl_add_u64 v[66:67], s[66:67], 2, v[66:67]
	s_lshl_b32 s74, s92, 2
	s_mov_b32 s75, s17
	v_lshl_add_u64 v[66:67], v[66:67], 0, s[74:75]
	global_store_dword v[66:67], v64, off
	s_cbranch_execnz .LBB0_643

.LBB0_654:
	s_andn2_b64 vcc, exec, s[70:71]
	s_cbranch_vccnz .LBB0_660
	s_waitcnt lgkmcnt(1)
	v_mul_f32_e32 v48, v45, v45
	v_mul_f32_e32 v49, v47, v47
	v_fmac_f32_e32 v48, v44, v44
	v_fmac_f32_e32 v49, v46, v46
	v_add_f32_e32 v48, v48, v49
	v_mul_f32_e32 v49, v41, v41
	v_mul_f32_e32 v50, v43, v43
	v_fmac_f32_e32 v49, v40, v40
	v_fmac_f32_e32 v50, v42, v42
	v_add_f32_e32 v49, v49, v50
	v_add_f32_e32 v48, v48, v49
	v_mul_f32_e32 v49, v37, v37
	v_mul_f32_e32 v50, v39, v39
	v_fmac_f32_e32 v49, v36, v36
	v_fmac_f32_e32 v50, v38, v38
	v_add_f32_e32 v49, v49, v50
	v_mul_f32_e32 v50, v33, v33
	v_mul_f32_e32 v51, v35, v35
	v_fmac_f32_e32 v50, v32, v32
	v_fmac_f32_e32 v51, v34, v34
	v_add_f32_e32 v50, v50, v51
	v_add_f32_e32 v49, v49, v50
	v_and_b32_e32 v50, 64, v191
	v_add_f32_e32 v48, v48, v49
	v_add_u32_e32 v50, 64, v50
	v_mov_b32_e32 v49, v48
	s_nop 1
	v_permlane16_swap_b32_e32 v48, v49
	s_waitcnt lgkmcnt(0)
	v_add_f32_e32 v48, v48, v49
	v_mov_b32_e32 v49, v48
	s_nop 1
	v_permlane32_swap_b32_e32 v48, v49
	s_and_saveexec_b64 s[70:71], s[4:5]
	s_cbranch_execz .LBB0_659
	s_andn2_b64 vcc, exec, s[64:65]
	s_waitcnt lgkmcnt(0)
	v_add_f32_e32 v48, v48, v49
	s_cbranch_vccnz .LBB0_712
	v_lshlrev_b64 v[50:51], 5, v[166:167]
	v_lshl_add_u64 v[50:51], s[40:41], 0, v[50:51]
	v_lshl_add_u64 v[50:51], s[66:67], 2, v[50:51]
	s_lshl_b32 s72, s92, 2
	s_mov_b32 s73, s17
	v_lshl_add_u64 v[50:51], v[50:51], 0, s[72:73]
	global_store_dword v[50:51], v48, off
	s_cbranch_execnz .LBB0_659

.LBB0_670:
	s_andn2_b64 vcc, exec, s[70:71]
	s_cbranch_vccnz .LBB0_676
	s_waitcnt lgkmcnt(1)
	v_mul_f32_e32 v32, v29, v29
	v_mul_f32_e32 v33, v31, v31
	v_fmac_f32_e32 v32, v28, v28
	v_fmac_f32_e32 v33, v30, v30
	v_add_f32_e32 v32, v32, v33
	v_mul_f32_e32 v33, v25, v25
	v_mul_f32_e32 v34, v27, v27
	v_fmac_f32_e32 v33, v24, v24
	v_fmac_f32_e32 v34, v26, v26
	v_add_f32_e32 v33, v33, v34
	v_add_f32_e32 v32, v32, v33
	v_mul_f32_e32 v33, v21, v21
	v_mul_f32_e32 v34, v23, v23
	v_fmac_f32_e32 v33, v20, v20
	v_fmac_f32_e32 v34, v22, v22
	v_add_f32_e32 v33, v33, v34
	v_mul_f32_e32 v34, v17, v17
	v_mul_f32_e32 v35, v19, v19
	v_fmac_f32_e32 v34, v16, v16
	v_fmac_f32_e32 v35, v18, v18
	v_add_f32_e32 v34, v34, v35
	v_add_f32_e32 v33, v33, v34
	v_and_b32_e32 v34, 64, v191
	v_add_f32_e32 v32, v32, v33
	v_add_u32_e32 v34, 64, v34
	v_mov_b32_e32 v33, v32
	s_nop 1
	v_permlane16_swap_b32_e32 v32, v33
	s_waitcnt lgkmcnt(0)
	v_add_f32_e32 v32, v32, v33
	v_mov_b32_e32 v33, v32
	s_nop 1
	v_permlane32_swap_b32_e32 v32, v33
	s_and_saveexec_b64 s[70:71], s[4:5]
	s_cbranch_execz .LBB0_675
	s_andn2_b64 vcc, exec, s[64:65]
	s_waitcnt lgkmcnt(0)
	v_add_f32_e32 v32, v32, v33
	s_cbranch_vccnz .LBB0_713
	v_lshlrev_b64 v[34:35], 5, v[162:163]
	v_lshl_add_u64 v[34:35], s[40:41], 0, v[34:35]
	v_lshl_add_u64 v[34:35], s[66:67], 2, v[34:35]
	s_lshl_b32 s72, s92, 2
	s_mov_b32 s73, s17
	v_lshl_add_u64 v[34:35], v[34:35], 0, s[72:73]
	global_store_dword v[34:35], v32, off
	s_cbranch_execnz .LBB0_675

.LBB0_686:
	s_andn2_b64 vcc, exec, s[10:11]
	s_cbranch_vccnz .LBB0_692
	s_waitcnt lgkmcnt(1)
	v_mul_f32_e32 v16, v13, v13
	v_mul_f32_e32 v17, v15, v15
	v_fmac_f32_e32 v16, v12, v12
	v_fmac_f32_e32 v17, v14, v14
	v_add_f32_e32 v16, v16, v17
	v_mul_f32_e32 v17, v9, v9
	v_mul_f32_e32 v18, v11, v11
	v_fmac_f32_e32 v17, v8, v8
	v_fmac_f32_e32 v18, v10, v10
	v_add_f32_e32 v17, v17, v18
	v_add_f32_e32 v16, v16, v17
	v_mul_f32_e32 v17, v5, v5
	v_mul_f32_e32 v18, v7, v7
	v_fmac_f32_e32 v17, v4, v4
	v_fmac_f32_e32 v18, v6, v6
	v_add_f32_e32 v17, v17, v18
	v_mul_f32_e32 v18, v1, v1
	v_mul_f32_e32 v19, v3, v3
	v_fmac_f32_e32 v18, v0, v0
	v_fmac_f32_e32 v19, v2, v2
	v_add_f32_e32 v18, v18, v19
	v_add_f32_e32 v17, v17, v18
	v_and_b32_e32 v18, 64, v191
	v_add_f32_e32 v16, v16, v17
	v_add_u32_e32 v18, 64, v18
	v_mov_b32_e32 v17, v16
	s_nop 1
	v_permlane16_swap_b32_e32 v16, v17
	s_waitcnt lgkmcnt(0)
	v_add_f32_e32 v16, v16, v17
	v_mov_b32_e32 v17, v16
	s_nop 1
	v_permlane32_swap_b32_e32 v16, v17
	s_and_saveexec_b64 s[8:9], s[4:5]
	s_cbranch_execz .LBB0_691
	s_andn2_b64 vcc, exec, s[64:65]
	s_waitcnt lgkmcnt(0)
	v_add_f32_e32 v16, v16, v17
	s_cbranch_vccnz .LBB0_714
	v_lshlrev_b64 v[18:19], 5, v[160:161]
	v_lshl_add_u64 v[18:19], s[40:41], 0, v[18:19]
	v_lshl_add_u64 v[18:19], s[66:67], 2, v[18:19]
	s_lshl_b32 s10, s92, 2
	s_mov_b32 s11, s17
	v_lshl_add_u64 v[18:19], v[18:19], 0, s[10:11]
	global_store_dword v[18:19], v16, off
	s_cbranch_execnz .LBB0_691

.LBB0_941:
	v_mbcnt_lo_u32_b32 v184, -1, 0
	v_mbcnt_hi_u32_b32 v184, -1, v184
	s_lshl_b32 s9, s34, 8
	v_ashrrev_i32_e32 v183, 3, v184
	v_add_u32_e32 v182, s60, v183
	v_add_u32_e32 v128, s9, v182
	v_ashrrev_i32_e32 v129, 31, v128
	s_lshl_b32 s36, s8, 8
	v_lshlrev_b64 v[128:129], 10, v[128:129]
	s_ashr_i32 s37, s36, 31
	v_lshl_add_u64 v[168:169], v[128:129], 0, s[36:37]
	v_or_b32_e32 v168, s66, v168
	v_lshlrev_b32_e32 v128, 4, v184
	v_and_b32_e32 v156, 0x70, v128
	v_lshl_add_u64 v[128:129], v[168:169], 1, s[12:13]
	v_lshl_add_u64 v[170:171], v[128:129], 0, v[156:157]
	v_add_co_u32_e32 v128, vcc, s55, v170
	v_mul_lo_u32 v183, v183, s71
	s_nop 0
	v_addc_co_u32_e32 v129, vcc, 0, v171, vcc
	global_load_dwordx4 v[186:189], v[170:171], off nt
	global_load_dwordx4 v[190:193], v[128:129], off nt
	v_add_co_u32_e32 v128, vcc, s64, v170
	v_add_u32_e32 v183, s70, v183
	s_nop 0
	v_addc_co_u32_e32 v129, vcc, 0, v171, vcc
	v_add_co_u32_e32 v130, vcc, s74, v170
	v_add_u32_e32 v183, v183, v156
	s_nop 0
	v_addc_co_u32_e32 v131, vcc, 0, v171, vcc
	v_add_co_u32_e32 v132, vcc, s53, v170
	v_add_u32_e32 v185, v174, v172
	s_nop 0
	v_addc_co_u32_e32 v133, vcc, 0, v171, vcc
	v_add_co_u32_e32 v134, vcc, s54, v170
	s_nop 1
	v_addc_co_u32_e32 v135, vcc, 0, v171, vcc
	v_add_co_u32_e32 v194, vcc, s63, v170
	s_nop 1
	v_addc_co_u32_e32 v195, vcc, 0, v171, vcc
	v_add_co_u32_e32 v196, vcc, s65, v170
	s_nop 1
	v_addc_co_u32_e32 v197, vcc, 0, v171, vcc
	global_load_dwordx4 v[144:147], v[128:129], off nt
	global_load_dwordx4 v[148:151], v[130:131], off nt
	global_load_dwordx4 v[136:139], v[132:133], off nt
	global_load_dwordx4 v[140:143], v[134:135], off nt
	s_nop 0
	global_load_dwordx4 v[128:131], v[194:195], off nt
	global_load_dwordx4 v[132:135], v[196:197], off nt
	s_waitcnt vmcnt(0)
	ds_write_b128 v183, v[186:189]
	ds_write_b128 v183, v[190:193] offset:1152
	ds_read_b128 v[186:189], v185
	ds_read_b128 v[190:193], v185 offset:64
	s_waitcnt lgkmcnt(1)
	v_lshlrev_b32_e32 v194, 16, v186
	v_and_b32_e32 v195, 0xffff0000, v186
	v_lshlrev_b32_e32 v186, 16, v187
	v_and_b32_e32 v187, 0xffff0000, v187
	v_lshlrev_b32_e32 v196, 16, v188
	v_and_b32_e32 v197, 0xffff0000, v188
	v_lshlrev_b32_e32 v188, 16, v189
	v_and_b32_e32 v189, 0xffff0000, v189
	s_waitcnt lgkmcnt(0)
	v_lshlrev_b32_e32 v198, 16, v190
	v_and_b32_e32 v199, 0xffff0000, v190
	v_lshlrev_b32_e32 v190, 16, v191
	v_and_b32_e32 v191, 0xffff0000, v191
	v_lshlrev_b32_e32 v200, 16, v192
	v_and_b32_e32 v201, 0xffff0000, v192
	v_lshlrev_b32_e32 v192, 16, v193
	v_and_b32_e32 v193, 0xffff0000, v193
	v_pk_add_f32 v[124:125], v[124:125], v[194:195]
	v_pk_add_f32 v[126:127], v[126:127], v[186:187]
	v_pk_add_f32 v[120:121], v[120:121], v[196:197]
	v_pk_add_f32 v[122:123], v[122:123], v[188:189]
	v_pk_add_f32 v[108:109], v[108:109], v[198:199]
	v_pk_add_f32 v[110:111], v[110:111], v[190:191]
	v_pk_add_f32 v[100:101], v[100:101], v[200:201]
	v_pk_add_f32 v[102:103], v[102:103], v[192:193]
	v_pk_mul_f32 v[186:187], v[124:125], v[124:125]
	v_pk_mul_f32 v[188:189], v[126:127], v[126:127]
	v_pk_mul_f32 v[190:191], v[120:121], v[120:121]
	v_pk_mul_f32 v[192:193], v[122:123], v[122:123]
	v_pk_mul_f32 v[194:195], v[108:109], v[108:109]
	v_pk_mul_f32 v[196:197], v[110:111], v[110:111]
	v_pk_mul_f32 v[198:199], v[100:101], v[100:101]
	v_pk_mul_f32 v[200:201], v[102:103], v[102:103]
	v_add_f32_e32 v198, v198, v199
	v_add_f32_e32 v156, v200, v201
	v_add_f32_e32 v196, v196, v197
	v_add_f32_e32 v194, v194, v195
	v_add_f32_e32 v192, v192, v193
	v_add_f32_e32 v190, v190, v191
	v_add_f32_e32 v188, v188, v189
	v_add_f32_e32 v186, v186, v187
	v_add_f32_e32 v156, v198, v156
	v_add_f32_e32 v187, v194, v196
	v_add_f32_e32 v189, v190, v192
	v_add_f32_e32 v186, v186, v188
	v_add_f32_e32 v156, v187, v156
	v_add_f32_e32 v186, v186, v189
	v_and_b32_e32 v187, 64, v178
	v_add_f32_e32 v186, v186, v156
	v_add_u32_e32 v188, 64, v187
	v_mov_b32_e32 v187, v186
	s_nop 1
	v_permlane16_swap_b32_e32 v186, v187
	s_waitcnt lgkmcnt(0)
	v_add_f32_e32 v187, v186, v187
	v_xor_b32_e32 v186, 32, v178
	v_cmp_lt_i32_e32 vcc, v186, v188
	s_nop 1
	v_cndmask_b32_e32 v186, v178, v186, vcc
	v_lshlrev_b32_e32 v186, 2, v186
	v_mov_b32_e32 v188, v187
	s_nop 1
	v_permlane32_swap_b32_e32 v187, v188
	s_and_saveexec_b64 s[6:7], s[0:1]
	s_cbranch_execz .LBB0_943
	s_waitcnt lgkmcnt(0)
	v_add_f32_e32 v187, v187, v188
	ds_write_b32 v180, v187
